# prep phase: all tile/weight loads of a workgroup issued up front (transposes, adaLN GEMV); forgetting-attention fast blocks: LDS reads issued together, plain-add row sums, SGPR-base tile loads
# speedup vs baseline: 1.0769x; 1.0101x over previous
.LBB0_47:
	s_andn2_b64 vcc, exec, s[6:7]
	s_cbranch_vccnz .LBB0_91
	s_cmpk_gt_i32 s2, 0x60
	s_mov_b64 s[6:7], -1
	s_cbranch_scc0 .LBB0_53
	s_cmpk_gt_u32 s2, 0x460
	s_cbranch_scc1 .LBB0_52
	v_add_u32_e32 v4, 0x200, v184
	v_lshrrev_b32_e32 v10, 6, v4
	v_add_u32_e32 v4, 0x600, v184
	v_lshrrev_b32_e32 v12, 6, v4
	v_add_u32_e32 v4, 0xa00, v184
	v_lshrrev_b32_e32 v14, 6, v4
	v_add_u32_e32 v4, 0xe00, v184
	v_lshlrev_b32_e32 v2, 3, v184
	v_and_b32_e32 v5, 63, v184
	v_lshrrev_b32_e32 v8, 6, v184
	v_lshrrev_b32_e32 v17, 6, v4
	s_movk_i32 s6, 0x1008
	v_mul_u32_u24_e32 v11, 0x104, v10
	v_mul_u32_u24_e32 v13, 0x104, v12
	v_mul_u32_u24_e32 v15, 0x104, v14
	v_and_b32_e32 v6, 56, v2
	v_mad_u32_u24 v2, v8, s6, v5
	v_mad_u32_u24 v10, v10, s6, v5
	v_mad_u32_u24 v12, v12, s6, v5
	v_mad_u32_u24 v14, v14, s6, v5
	v_mad_u32_u24 v18, v17, s6, v5
	v_readlane_b32 s6, v247, 0
	v_readlane_b32 s7, v247, 1
	s_load_dwordx2 s[6:7], s[6:7], 0x60
	v_mov_b32_e32 v3, 0x100
	v_lshrrev_b32_e32 v4, 3, v184
	v_lshl_add_u32 v7, v5, 2, v3
	v_mul_u32_u24_e32 v9, 0x104, v8
	v_lshl_add_u32 v20, v4, 2, v3
	v_mul_u32_u24_e32 v21, 0x104, v6
	v_add_u32_e32 v16, 0x30180, v2
	s_add_u32 s10, s84, 0x175100
	v_mul_u32_u24_e32 v19, 0x104, v17
	v_lshlrev_b32_e32 v4, 10, v4
	v_mov_b32_e32 v3, 0
	s_addc_u32 s11, s85, 0
	s_lshl_b32 s8, s2, 6
	s_lshl_b32 s13, s86, 6
	v_add_u32_e32 v8, v7, v9
	v_lshlrev_b32_e32 v9, 2, v10
	v_add_u32_e32 v10, v7, v11
	v_lshlrev_b32_e32 v11, 2, v12
	v_add_u32_e32 v12, v7, v13
	v_lshlrev_b32_e32 v13, 2, v14
	v_add_u32_e32 v14, v7, v15
	v_lshlrev_b32_e32 v15, 2, v16
	v_lshlrev_b32_e32 v16, 2, v18
	v_add_u32_e32 v18, v20, v21
	s_add_i32 s12, s8, 0xffffe7c0
	s_addk_i32 s13, 0xe7c0
	s_mov_b32 s9, 0
	v_lshlrev_b32_e32 v2, 2, v2
	s_mov_b32 s14, 0x40000
	s_mov_b32 s15, 0x80000
	v_add_u32_e32 v17, v7, v19
	v_lshlrev_b32_e32 v4, 1, v4
	v_mov_b32_e32 v5, v3
	v_lshlrev_b32_e32 v6, 1, v6
	v_mov_b32_e32 v7, v3
	v_add_u32_e32 v19, 0x400, v18
	s_mov_b32 s8, s2
	s_add_i32 s18, s8, 0xffffff9f
	s_and_b32 s19, s12, 0xfc0
	s_and_b32 s8, s18, 0xffffffc0
	s_or_b32 s16, s19, 8
	s_cmpk_lt_u32 s19, 0xe00
	s_mul_i32 s20, s8, 0x4020
	s_mul_hi_u32 s17, s8, 0x4020
	s_cselect_b32 s16, s19, s16
	s_waitcnt lgkmcnt(0)
	s_add_u32 s20, s6, s20
	s_addc_u32 s17, s7, s17
	s_lshl_b32 s16, s16, 2
	s_add_u32 s16, s20, s16
	s_addc_u32 s17, s17, 0
	v_lshl_add_u64 v[20:21], s[16:17], 0, v[2:3]
	v_add_co_u32_e32 v22, vcc, s14, v20
	global_load_dword v186, v2, s[16:17]
	global_load_dword v187, v9, s[16:17]
	v_addc_co_u32_e32 v23, vcc, 0, v21, vcc
	v_add_co_u32_e32 v20, vcc, s15, v20
	s_nop 1
	v_addc_co_u32_e32 v21, vcc, 0, v21, vcc
	global_load_dword v188, v[22:23], off offset:512
	global_load_dword v189, v11, s[16:17]
	global_load_dword v190, v[20:21], off offset:1024
	global_load_dword v191, v13, s[16:17]
	global_load_dword v192, v15, s[16:17]
	global_load_dword v193, v16, s[16:17]
	s_lshl_b32 s16, s19, 11
	s_add_u32 s19, s10, s16
	s_addc_u32 s20, s11, 0
	s_lshl_b64 s[16:17], s[8:9], 1
	s_add_u32 s16, s19, s16
	s_addc_u32 s17, s20, s17
	v_lshl_add_u64 v[20:21], s[16:17], 0, v[4:5]
	v_lshl_add_u64 v[164:165], v[20:21], 0, v[6:7]
	s_add_i32 s8, s18, s86
	s_add_i32 s12, s12, s13
	s_cmpk_gt_i32 s8, 0x460
	s_cbranch_scc1 .Ltr_i1
	s_add_i32 s18, s8, 0xffffff9f
	s_and_b32 s19, s12, 0xfc0
	s_and_b32 s8, s18, 0xffffffc0
	s_or_b32 s16, s19, 8
	s_cmpk_lt_u32 s19, 0xe00
	s_mul_i32 s20, s8, 0x4020
	s_mul_hi_u32 s17, s8, 0x4020
	s_cselect_b32 s16, s19, s16
	s_waitcnt lgkmcnt(0)
	s_add_u32 s20, s6, s20
	s_addc_u32 s17, s7, s17
	s_lshl_b32 s16, s16, 2
	s_add_u32 s16, s20, s16
	s_addc_u32 s17, s17, 0
	v_lshl_add_u64 v[20:21], s[16:17], 0, v[2:3]
	v_add_co_u32_e32 v22, vcc, s14, v20
	global_load_dword v194, v2, s[16:17]
	global_load_dword v195, v9, s[16:17]
	v_addc_co_u32_e32 v23, vcc, 0, v21, vcc
	v_add_co_u32_e32 v20, vcc, s15, v20
	s_nop 1
	v_addc_co_u32_e32 v21, vcc, 0, v21, vcc
	global_load_dword v196, v[22:23], off offset:512
	global_load_dword v197, v11, s[16:17]
	global_load_dword v198, v[20:21], off offset:1024
	global_load_dword v199, v13, s[16:17]
	global_load_dword v200, v15, s[16:17]
	global_load_dword v201, v16, s[16:17]
	s_lshl_b32 s16, s19, 11
	s_add_u32 s19, s10, s16
	s_addc_u32 s20, s11, 0
	s_lshl_b64 s[16:17], s[8:9], 1
	s_add_u32 s16, s19, s16
	s_addc_u32 s17, s20, s17
	v_lshl_add_u64 v[20:21], s[16:17], 0, v[4:5]
	v_lshl_add_u64 v[166:167], v[20:21], 0, v[6:7]
	s_add_i32 s8, s18, s86
	s_add_i32 s12, s12, s13
	s_cmpk_gt_i32 s8, 0x460
	s_cbranch_scc1 .Ltr_i2
	s_add_i32 s18, s8, 0xffffff9f
	s_and_b32 s19, s12, 0xfc0
	s_and_b32 s8, s18, 0xffffffc0
	s_or_b32 s16, s19, 8
	s_cmpk_lt_u32 s19, 0xe00
	s_mul_i32 s20, s8, 0x4020
	s_mul_hi_u32 s17, s8, 0x4020
	s_cselect_b32 s16, s19, s16
	s_waitcnt lgkmcnt(0)
	s_add_u32 s20, s6, s20
	s_addc_u32 s17, s7, s17
	s_lshl_b32 s16, s16, 2
	s_add_u32 s16, s20, s16
	s_addc_u32 s17, s17, 0
	v_lshl_add_u64 v[20:21], s[16:17], 0, v[2:3]
	v_add_co_u32_e32 v22, vcc, s14, v20
	global_load_dword v202, v2, s[16:17]
	global_load_dword v203, v9, s[16:17]
	v_addc_co_u32_e32 v23, vcc, 0, v21, vcc
	v_add_co_u32_e32 v20, vcc, s15, v20
	s_nop 1
	v_addc_co_u32_e32 v21, vcc, 0, v21, vcc
	global_load_dword v204, v[22:23], off offset:512
	global_load_dword v205, v11, s[16:17]
	global_load_dword v206, v[20:21], off offset:1024
	global_load_dword v207, v13, s[16:17]
	global_load_dword v208, v15, s[16:17]
	global_load_dword v209, v16, s[16:17]
	s_lshl_b32 s16, s19, 11
	s_add_u32 s19, s10, s16
	s_addc_u32 s20, s11, 0
	s_lshl_b64 s[16:17], s[8:9], 1
	s_add_u32 s16, s19, s16
	s_addc_u32 s17, s20, s17
	v_lshl_add_u64 v[20:21], s[16:17], 0, v[4:5]
	v_lshl_add_u64 v[168:169], v[20:21], 0, v[6:7]
	s_add_i32 s8, s18, s86
	s_add_i32 s12, s12, s13
	s_cmpk_gt_i32 s8, 0x460
	s_cbranch_scc1 .Ltr_i3
	s_add_i32 s18, s8, 0xffffff9f
	s_and_b32 s19, s12, 0xfc0
	s_and_b32 s8, s18, 0xffffffc0
	s_or_b32 s16, s19, 8
	s_cmpk_lt_u32 s19, 0xe00
	s_mul_i32 s20, s8, 0x4020
	s_mul_hi_u32 s17, s8, 0x4020
	s_cselect_b32 s16, s19, s16
	s_waitcnt lgkmcnt(0)
	s_add_u32 s20, s6, s20
	s_addc_u32 s17, s7, s17
	s_lshl_b32 s16, s16, 2
	s_add_u32 s16, s20, s16
	s_addc_u32 s17, s17, 0
	v_lshl_add_u64 v[20:21], s[16:17], 0, v[2:3]
	v_add_co_u32_e32 v22, vcc, s14, v20
	global_load_dword v210, v2, s[16:17]
	global_load_dword v211, v9, s[16:17]
	v_addc_co_u32_e32 v23, vcc, 0, v21, vcc
	v_add_co_u32_e32 v20, vcc, s15, v20
	s_nop 1
	v_addc_co_u32_e32 v21, vcc, 0, v21, vcc
	global_load_dword v212, v[22:23], off offset:512
	global_load_dword v213, v11, s[16:17]
	global_load_dword v214, v[20:21], off offset:1024
	global_load_dword v215, v13, s[16:17]
	global_load_dword v216, v15, s[16:17]
	global_load_dword v217, v16, s[16:17]
	s_lshl_b32 s16, s19, 11
	s_add_u32 s19, s10, s16
	s_addc_u32 s20, s11, 0
	s_lshl_b64 s[16:17], s[8:9], 1
	s_add_u32 s16, s19, s16
	s_addc_u32 s17, s20, s17
	v_lshl_add_u64 v[20:21], s[16:17], 0, v[4:5]
	v_lshl_add_u64 v[170:171], v[20:21], 0, v[6:7]
	s_add_i32 s8, s18, s86
	s_add_i32 s12, s12, s13
	s_cmpk_gt_i32 s8, 0x460
	s_cbranch_scc1 .Ltr_i4
	s_add_i32 s18, s8, 0xffffff9f
	s_and_b32 s19, s12, 0xfc0
	s_and_b32 s8, s18, 0xffffffc0
	s_or_b32 s16, s19, 8
	s_cmpk_lt_u32 s19, 0xe00
	s_mul_i32 s20, s8, 0x4020
	s_mul_hi_u32 s17, s8, 0x4020
	s_cselect_b32 s16, s19, s16
	s_waitcnt lgkmcnt(0)
	s_add_u32 s20, s6, s20
	s_addc_u32 s17, s7, s17
	s_lshl_b32 s16, s16, 2
	s_add_u32 s16, s20, s16
	s_addc_u32 s17, s17, 0
	v_lshl_add_u64 v[20:21], s[16:17], 0, v[2:3]
	v_add_co_u32_e32 v22, vcc, s14, v20
	global_load_dword v218, v2, s[16:17]
	global_load_dword v219, v9, s[16:17]
	v_addc_co_u32_e32 v23, vcc, 0, v21, vcc
	v_add_co_u32_e32 v20, vcc, s15, v20
	s_nop 1
	v_addc_co_u32_e32 v21, vcc, 0, v21, vcc
	global_load_dword v220, v[22:23], off offset:512
	global_load_dword v221, v11, s[16:17]
	global_load_dword v222, v[20:21], off offset:1024
	global_load_dword v223, v13, s[16:17]
	global_load_dword v224, v15, s[16:17]
	global_load_dword v225, v16, s[16:17]
	s_lshl_b32 s16, s19, 11
	s_add_u32 s19, s10, s16
	s_addc_u32 s20, s11, 0
	s_lshl_b64 s[16:17], s[8:9], 1
	s_add_u32 s16, s19, s16
	s_addc_u32 s17, s20, s17
	v_lshl_add_u64 v[20:21], s[16:17], 0, v[4:5]
	v_lshl_add_u64 v[172:173], v[20:21], 0, v[6:7]
	s_add_i32 s8, s18, s86
	s_add_i32 s12, s12, s13
	s_cmpk_gt_i32 s8, 0x460
	s_cbranch_scc1 .Ltr_i5
	s_add_i32 s18, s8, 0xffffff9f
	s_and_b32 s19, s12, 0xfc0
	s_and_b32 s8, s18, 0xffffffc0
	s_or_b32 s16, s19, 8
	s_cmpk_lt_u32 s19, 0xe00
	s_mul_i32 s20, s8, 0x4020
	s_mul_hi_u32 s17, s8, 0x4020
	s_cselect_b32 s16, s19, s16
	s_waitcnt lgkmcnt(0)
	s_add_u32 s20, s6, s20
	s_addc_u32 s17, s7, s17
	s_lshl_b32 s16, s16, 2
	s_add_u32 s16, s20, s16
	s_addc_u32 s17, s17, 0
	v_lshl_add_u64 v[20:21], s[16:17], 0, v[2:3]
	v_add_co_u32_e32 v22, vcc, s14, v20
	global_load_dword v226, v2, s[16:17]
	global_load_dword v227, v9, s[16:17]
	v_addc_co_u32_e32 v23, vcc, 0, v21, vcc
	v_add_co_u32_e32 v20, vcc, s15, v20
	s_nop 1
	v_addc_co_u32_e32 v21, vcc, 0, v21, vcc
	global_load_dword v228, v[22:23], off offset:512
	global_load_dword v229, v11, s[16:17]
	global_load_dword v230, v[20:21], off offset:1024
	global_load_dword v231, v13, s[16:17]
	global_load_dword v232, v15, s[16:17]
	global_load_dword v233, v16, s[16:17]
	s_lshl_b32 s16, s19, 11
	s_add_u32 s19, s10, s16
	s_addc_u32 s20, s11, 0
	s_lshl_b64 s[16:17], s[8:9], 1
	s_add_u32 s16, s19, s16
	s_addc_u32 s17, s20, s17
	v_lshl_add_u64 v[20:21], s[16:17], 0, v[4:5]
	v_lshl_add_u64 v[174:175], v[20:21], 0, v[6:7]
	s_add_i32 s8, s18, s86
	s_add_i32 s12, s12, s13
	s_cmpk_gt_i32 s8, 0x460
	s_cbranch_scc1 .Ltr_i6
	s_add_i32 s18, s8, 0xffffff9f
	s_and_b32 s19, s12, 0xfc0
	s_and_b32 s8, s18, 0xffffffc0
	s_or_b32 s16, s19, 8
	s_cmpk_lt_u32 s19, 0xe00
	s_mul_i32 s20, s8, 0x4020
	s_mul_hi_u32 s17, s8, 0x4020
	s_cselect_b32 s16, s19, s16
	s_waitcnt lgkmcnt(0)
	s_add_u32 s20, s6, s20
	s_addc_u32 s17, s7, s17
	s_lshl_b32 s16, s16, 2
	s_add_u32 s16, s20, s16
	s_addc_u32 s17, s17, 0
	v_lshl_add_u64 v[20:21], s[16:17], 0, v[2:3]
	v_add_co_u32_e32 v22, vcc, s14, v20
	global_load_dword v234, v2, s[16:17]
	global_load_dword v235, v9, s[16:17]
	v_addc_co_u32_e32 v23, vcc, 0, v21, vcc
	v_add_co_u32_e32 v20, vcc, s15, v20
	s_nop 1
	v_addc_co_u32_e32 v21, vcc, 0, v21, vcc
	global_load_dword v236, v[22:23], off offset:512
	global_load_dword v237, v11, s[16:17]
	global_load_dword v238, v[20:21], off offset:1024
	global_load_dword v239, v13, s[16:17]
	global_load_dword v240, v15, s[16:17]
	global_load_dword v241, v16, s[16:17]
	s_lshl_b32 s16, s19, 11
	s_add_u32 s19, s10, s16
	s_addc_u32 s20, s11, 0
	s_lshl_b64 s[16:17], s[8:9], 1
	s_add_u32 s16, s19, s16
	s_addc_u32 s17, s20, s17
	v_lshl_add_u64 v[20:21], s[16:17], 0, v[4:5]
	v_lshl_add_u64 v[176:177], v[20:21], 0, v[6:7]
	s_add_i32 s8, s18, s86
	s_add_i32 s12, s12, s13
	s_cmpk_gt_i32 s8, 0x460
	s_mov_b32 s99, 7
	s_branch .Ltr_p2
.Ltr_i1:
	s_mov_b32 s99, 1
	s_branch .Ltr_p2
.Ltr_i2:
	s_mov_b32 s99, 2
	s_branch .Ltr_p2
.Ltr_i3:
	s_mov_b32 s99, 3
	s_branch .Ltr_p2
.Ltr_i4:
	s_mov_b32 s99, 4
	s_branch .Ltr_p2
.Ltr_i5:
	s_mov_b32 s99, 5
	s_branch .Ltr_p2
.Ltr_i6:
	s_mov_b32 s99, 6
.Ltr_p2:
	s_waitcnt vmcnt(0)
	ds_write_b32 v8, v186
	ds_write_b32 v10, v187
	ds_write_b32 v8, v188 offset:4160
	ds_write_b32 v12, v189
	ds_write_b32 v8, v190 offset:8320
	ds_write_b32 v14, v191
	ds_write_b32 v8, v192 offset:12480
	ds_write_b32 v17, v193
	s_waitcnt lgkmcnt(0)
	s_barrier
	ds_read2_b32 v[20:21], v18 offset1:65
	ds_read2_b32 v[22:23], v18 offset0:130 offset1:195
	ds_read2_b32 v[26:27], v19 offset0:4 offset1:69
	ds_read2_b32 v[28:29], v19 offset0:134 offset1:199
	s_waitcnt lgkmcnt(3)
	v_cvt_pk_bf16_f32 v20, v20, v21
	s_waitcnt lgkmcnt(2)
	v_cvt_pk_bf16_f32 v21, v22, v23
	s_waitcnt lgkmcnt(1)
	v_cvt_pk_bf16_f32 v22, v26, v27
	s_waitcnt lgkmcnt(0)
	v_cvt_pk_bf16_f32 v23, v28, v29
	global_store_dwordx4 v[164:165], v[20:23], off
	s_barrier
	s_cmp_lt_u32 s99, 2
	s_cbranch_scc1 .Ltr_done
	ds_write_b32 v8, v194
	ds_write_b32 v10, v195
	ds_write_b32 v8, v196 offset:4160
	ds_write_b32 v12, v197
	ds_write_b32 v8, v198 offset:8320
	ds_write_b32 v14, v199
	ds_write_b32 v8, v200 offset:12480
	ds_write_b32 v17, v201
	s_waitcnt lgkmcnt(0)
	s_barrier
	ds_read2_b32 v[20:21], v18 offset1:65
	ds_read2_b32 v[22:23], v18 offset0:130 offset1:195
	ds_read2_b32 v[26:27], v19 offset0:4 offset1:69
	ds_read2_b32 v[28:29], v19 offset0:134 offset1:199
	s_waitcnt lgkmcnt(3)
	v_cvt_pk_bf16_f32 v20, v20, v21
	s_waitcnt lgkmcnt(2)
	v_cvt_pk_bf16_f32 v21, v22, v23
	s_waitcnt lgkmcnt(1)
	v_cvt_pk_bf16_f32 v22, v26, v27
	s_waitcnt lgkmcnt(0)
	v_cvt_pk_bf16_f32 v23, v28, v29
	global_store_dwordx4 v[166:167], v[20:23], off
	s_barrier
	s_cmp_lt_u32 s99, 3
	s_cbranch_scc1 .Ltr_done
	ds_write_b32 v8, v202
	ds_write_b32 v10, v203
	ds_write_b32 v8, v204 offset:4160
	ds_write_b32 v12, v205
	ds_write_b32 v8, v206 offset:8320
	ds_write_b32 v14, v207
	ds_write_b32 v8, v208 offset:12480
	ds_write_b32 v17, v209
	s_waitcnt lgkmcnt(0)
	s_barrier
	ds_read2_b32 v[20:21], v18 offset1:65
	ds_read2_b32 v[22:23], v18 offset0:130 offset1:195
	ds_read2_b32 v[26:27], v19 offset0:4 offset1:69
	ds_read2_b32 v[28:29], v19 offset0:134 offset1:199
	s_waitcnt lgkmcnt(3)
	v_cvt_pk_bf16_f32 v20, v20, v21
	s_waitcnt lgkmcnt(2)
	v_cvt_pk_bf16_f32 v21, v22, v23
	s_waitcnt lgkmcnt(1)
	v_cvt_pk_bf16_f32 v22, v26, v27
	s_waitcnt lgkmcnt(0)
	v_cvt_pk_bf16_f32 v23, v28, v29
	global_store_dwordx4 v[168:169], v[20:23], off
	s_barrier
	s_cmp_lt_u32 s99, 4
	s_cbranch_scc1 .Ltr_done
	ds_write_b32 v8, v210
	ds_write_b32 v10, v211
	ds_write_b32 v8, v212 offset:4160
	ds_write_b32 v12, v213
	ds_write_b32 v8, v214 offset:8320
	ds_write_b32 v14, v215
	ds_write_b32 v8, v216 offset:12480
	ds_write_b32 v17, v217
	s_waitcnt lgkmcnt(0)
	s_barrier
	ds_read2_b32 v[20:21], v18 offset1:65
	ds_read2_b32 v[22:23], v18 offset0:130 offset1:195
	ds_read2_b32 v[26:27], v19 offset0:4 offset1:69
	ds_read2_b32 v[28:29], v19 offset0:134 offset1:199
	s_waitcnt lgkmcnt(3)
	v_cvt_pk_bf16_f32 v20, v20, v21
	s_waitcnt lgkmcnt(2)
	v_cvt_pk_bf16_f32 v21, v22, v23
	s_waitcnt lgkmcnt(1)
	v_cvt_pk_bf16_f32 v22, v26, v27
	s_waitcnt lgkmcnt(0)
	v_cvt_pk_bf16_f32 v23, v28, v29
	global_store_dwordx4 v[170:171], v[20:23], off
	s_barrier
	s_cmp_lt_u32 s99, 5
	s_cbranch_scc1 .Ltr_done
	ds_write_b32 v8, v218
	ds_write_b32 v10, v219
	ds_write_b32 v8, v220 offset:4160
	ds_write_b32 v12, v221
	ds_write_b32 v8, v222 offset:8320
	ds_write_b32 v14, v223
	ds_write_b32 v8, v224 offset:12480
	ds_write_b32 v17, v225
	s_waitcnt lgkmcnt(0)
	s_barrier
	ds_read2_b32 v[20:21], v18 offset1:65
	ds_read2_b32 v[22:23], v18 offset0:130 offset1:195
	ds_read2_b32 v[26:27], v19 offset0:4 offset1:69
	ds_read2_b32 v[28:29], v19 offset0:134 offset1:199
	s_waitcnt lgkmcnt(3)
	v_cvt_pk_bf16_f32 v20, v20, v21
	s_waitcnt lgkmcnt(2)
	v_cvt_pk_bf16_f32 v21, v22, v23
	s_waitcnt lgkmcnt(1)
	v_cvt_pk_bf16_f32 v22, v26, v27
	s_waitcnt lgkmcnt(0)
	v_cvt_pk_bf16_f32 v23, v28, v29
	global_store_dwordx4 v[172:173], v[20:23], off
	s_barrier
	s_cmp_lt_u32 s99, 6
	s_cbranch_scc1 .Ltr_done
	ds_write_b32 v8, v226
	ds_write_b32 v10, v227
	ds_write_b32 v8, v228 offset:4160
	ds_write_b32 v12, v229
	ds_write_b32 v8, v230 offset:8320
	ds_write_b32 v14, v231
	ds_write_b32 v8, v232 offset:12480
	ds_write_b32 v17, v233
	s_waitcnt lgkmcnt(0)
	s_barrier
	ds_read2_b32 v[20:21], v18 offset1:65
	ds_read2_b32 v[22:23], v18 offset0:130 offset1:195
	ds_read2_b32 v[26:27], v19 offset0:4 offset1:69
	ds_read2_b32 v[28:29], v19 offset0:134 offset1:199
	s_waitcnt lgkmcnt(3)
	v_cvt_pk_bf16_f32 v20, v20, v21
	s_waitcnt lgkmcnt(2)
	v_cvt_pk_bf16_f32 v21, v22, v23
	s_waitcnt lgkmcnt(1)
	v_cvt_pk_bf16_f32 v22, v26, v27
	s_waitcnt lgkmcnt(0)
	v_cvt_pk_bf16_f32 v23, v28, v29
	global_store_dwordx4 v[174:175], v[20:23], off
	s_barrier
	s_cmp_lt_u32 s99, 7
	s_cbranch_scc1 .Ltr_done
	ds_write_b32 v8, v234
	ds_write_b32 v10, v235
	ds_write_b32 v8, v236 offset:4160
	ds_write_b32 v12, v237
	ds_write_b32 v8, v238 offset:8320
	ds_write_b32 v14, v239
	ds_write_b32 v8, v240 offset:12480
	ds_write_b32 v17, v241
	s_waitcnt lgkmcnt(0)
	s_barrier
	ds_read2_b32 v[20:21], v18 offset1:65
	ds_read2_b32 v[22:23], v18 offset0:130 offset1:195
	ds_read2_b32 v[26:27], v19 offset0:4 offset1:69
	ds_read2_b32 v[28:29], v19 offset0:134 offset1:199
	s_waitcnt lgkmcnt(3)
	v_cvt_pk_bf16_f32 v20, v20, v21
	s_waitcnt lgkmcnt(2)
	v_cvt_pk_bf16_f32 v21, v22, v23
	s_waitcnt lgkmcnt(1)
	v_cvt_pk_bf16_f32 v22, v26, v27
	s_waitcnt lgkmcnt(0)
	v_cvt_pk_bf16_f32 v23, v28, v29
	global_store_dwordx4 v[176:177], v[20:23], off
	s_barrier
.Ltr_done:
	s_cmpk_gt_i32 s8, 0x460
	s_cbranch_scc1 .LBB0_52

.LBB0_87:
	s_or_b64 exec, exec, s[18:19]
	v_ashrrev_i32_e32 v99, 31, v98
	v_mov_b32_e32 v102, 0
	v_lshl_add_u64 v[100:101], v[98:99], 2, v[96:97]
	s_mov_b32 s21, 0
	global_load_dword v186, v[100:101], off
	s_mov_b32 s20, 0x3000
	v_lshl_add_u64 v[110:111], v[100:101], 0, s[20:21]
	global_load_dword v187, v[110:111], off
	s_mov_b32 s20, 0x6000
	v_lshl_add_u64 v[110:111], v[100:101], 0, s[20:21]
	global_load_dword v188, v[110:111], off
	s_mov_b32 s20, 0x9000
	v_lshl_add_u64 v[110:111], v[100:101], 0, s[20:21]
	global_load_dword v189, v[110:111], off
	s_mov_b32 s20, 0xc000
	v_lshl_add_u64 v[110:111], v[100:101], 0, s[20:21]
	global_load_dword v190, v[110:111], off
	s_mov_b32 s20, 0xf000
	v_lshl_add_u64 v[110:111], v[100:101], 0, s[20:21]
	global_load_dword v191, v[110:111], off
	s_mov_b32 s20, 0x12000
	v_lshl_add_u64 v[110:111], v[100:101], 0, s[20:21]
	global_load_dword v192, v[110:111], off
	s_mov_b32 s20, 0x15000
	v_lshl_add_u64 v[110:111], v[100:101], 0, s[20:21]
	global_load_dword v193, v[110:111], off
	s_mov_b32 s20, 0x18000
	v_lshl_add_u64 v[110:111], v[100:101], 0, s[20:21]
	global_load_dword v194, v[110:111], off
	s_mov_b32 s20, 0x1b000
	v_lshl_add_u64 v[110:111], v[100:101], 0, s[20:21]
	global_load_dword v195, v[110:111], off
	s_mov_b32 s20, 0x1e000
	v_lshl_add_u64 v[110:111], v[100:101], 0, s[20:21]
	global_load_dword v196, v[110:111], off
	s_mov_b32 s20, 0x21000
	v_lshl_add_u64 v[110:111], v[100:101], 0, s[20:21]
	global_load_dword v197, v[110:111], off
	s_mov_b32 s20, 0x24000
	v_lshl_add_u64 v[110:111], v[100:101], 0, s[20:21]
	global_load_dword v198, v[110:111], off
	s_mov_b32 s20, 0x27000
	v_lshl_add_u64 v[110:111], v[100:101], 0, s[20:21]
	global_load_dword v199, v[110:111], off
	s_mov_b32 s20, 0x2a000
	v_lshl_add_u64 v[110:111], v[100:101], 0, s[20:21]
	global_load_dword v200, v[110:111], off
	s_mov_b32 s20, 0x2d000
	v_lshl_add_u64 v[110:111], v[100:101], 0, s[20:21]
	global_load_dword v201, v[110:111], off
	s_mov_b32 s20, 0x30000
	v_lshl_add_u64 v[110:111], v[100:101], 0, s[20:21]
	global_load_dword v202, v[110:111], off
	s_mov_b32 s20, 0x33000
	v_lshl_add_u64 v[110:111], v[100:101], 0, s[20:21]
	global_load_dword v203, v[110:111], off
	s_mov_b32 s20, 0x36000
	v_lshl_add_u64 v[110:111], v[100:101], 0, s[20:21]
	global_load_dword v204, v[110:111], off
	s_mov_b32 s20, 0x39000
	v_lshl_add_u64 v[110:111], v[100:101], 0, s[20:21]
	global_load_dword v205, v[110:111], off
	s_mov_b32 s20, 0x3c000
	v_lshl_add_u64 v[110:111], v[100:101], 0, s[20:21]
	global_load_dword v206, v[110:111], off
	s_mov_b32 s20, 0x3f000
	v_lshl_add_u64 v[110:111], v[100:101], 0, s[20:21]
	global_load_dword v207, v[110:111], off
	s_mov_b32 s20, 0x42000
	v_lshl_add_u64 v[110:111], v[100:101], 0, s[20:21]
	global_load_dword v208, v[110:111], off
	s_mov_b32 s20, 0x45000
	v_lshl_add_u64 v[110:111], v[100:101], 0, s[20:21]
	global_load_dword v209, v[110:111], off
	s_mov_b32 s20, 0x48000
	v_lshl_add_u64 v[110:111], v[100:101], 0, s[20:21]
	global_load_dword v210, v[110:111], off
	s_mov_b32 s20, 0x4b000
	v_lshl_add_u64 v[110:111], v[100:101], 0, s[20:21]
	global_load_dword v211, v[110:111], off
	s_mov_b32 s20, 0x4e000
	v_lshl_add_u64 v[110:111], v[100:101], 0, s[20:21]
	global_load_dword v212, v[110:111], off
	s_mov_b32 s20, 0x51000
	v_lshl_add_u64 v[110:111], v[100:101], 0, s[20:21]
	global_load_dword v213, v[110:111], off
	s_mov_b32 s20, 0x54000
	v_lshl_add_u64 v[110:111], v[100:101], 0, s[20:21]
	global_load_dword v214, v[110:111], off
	s_mov_b32 s20, 0x57000
	v_lshl_add_u64 v[110:111], v[100:101], 0, s[20:21]
	global_load_dword v215, v[110:111], off
	s_mov_b32 s20, 0x5a000
	v_lshl_add_u64 v[110:111], v[100:101], 0, s[20:21]
	global_load_dword v216, v[110:111], off
	s_mov_b32 s20, 0x5d000
	v_lshl_add_u64 v[110:111], v[100:101], 0, s[20:21]
	global_load_dword v217, v[110:111], off
	s_mov_b32 s20, 0x60000
	v_lshl_add_u64 v[110:111], v[100:101], 0, s[20:21]
	global_load_dword v218, v[110:111], off
	s_mov_b32 s20, 0x63000
	v_lshl_add_u64 v[110:111], v[100:101], 0, s[20:21]
	global_load_dword v219, v[110:111], off
	s_mov_b32 s20, 0x66000
	v_lshl_add_u64 v[110:111], v[100:101], 0, s[20:21]
	global_load_dword v220, v[110:111], off
	s_mov_b32 s20, 0x69000
	v_lshl_add_u64 v[110:111], v[100:101], 0, s[20:21]
	global_load_dword v221, v[110:111], off
	s_mov_b32 s20, 0x6c000
	v_lshl_add_u64 v[110:111], v[100:101], 0, s[20:21]
	global_load_dword v222, v[110:111], off
	s_mov_b32 s20, 0x6f000
	v_lshl_add_u64 v[110:111], v[100:101], 0, s[20:21]
	global_load_dword v223, v[110:111], off
	s_mov_b32 s20, 0x72000
	v_lshl_add_u64 v[110:111], v[100:101], 0, s[20:21]
	global_load_dword v224, v[110:111], off
	s_mov_b32 s20, 0x75000
	v_lshl_add_u64 v[110:111], v[100:101], 0, s[20:21]
	global_load_dword v225, v[110:111], off
	s_mov_b32 s20, 0x78000
	v_lshl_add_u64 v[110:111], v[100:101], 0, s[20:21]
	global_load_dword v226, v[110:111], off
	s_mov_b32 s20, 0x7b000
	v_lshl_add_u64 v[110:111], v[100:101], 0, s[20:21]
	global_load_dword v227, v[110:111], off
	s_mov_b32 s20, 0x7e000
	v_lshl_add_u64 v[110:111], v[100:101], 0, s[20:21]
	global_load_dword v228, v[110:111], off
	s_mov_b32 s20, 0x81000
	v_lshl_add_u64 v[110:111], v[100:101], 0, s[20:21]
	global_load_dword v229, v[110:111], off
	s_mov_b32 s20, 0x84000
	v_lshl_add_u64 v[110:111], v[100:101], 0, s[20:21]
	global_load_dword v230, v[110:111], off
	s_mov_b32 s20, 0x87000
	v_lshl_add_u64 v[110:111], v[100:101], 0, s[20:21]
	global_load_dword v231, v[110:111], off
	s_mov_b32 s20, 0x8a000
	v_lshl_add_u64 v[110:111], v[100:101], 0, s[20:21]
	global_load_dword v232, v[110:111], off
	s_mov_b32 s20, 0x8d000
	v_lshl_add_u64 v[110:111], v[100:101], 0, s[20:21]
	global_load_dword v233, v[110:111], off
	s_mov_b32 s20, 0x90000
	v_lshl_add_u64 v[110:111], v[100:101], 0, s[20:21]
	global_load_dword v234, v[110:111], off
	s_mov_b32 s20, 0x93000
	v_lshl_add_u64 v[110:111], v[100:101], 0, s[20:21]
	global_load_dword v235, v[110:111], off
	s_mov_b32 s20, 0x96000
	v_lshl_add_u64 v[110:111], v[100:101], 0, s[20:21]
	global_load_dword v236, v[110:111], off
	s_mov_b32 s20, 0x99000
	v_lshl_add_u64 v[110:111], v[100:101], 0, s[20:21]
	global_load_dword v237, v[110:111], off
	s_mov_b32 s20, 0x9c000
	v_lshl_add_u64 v[110:111], v[100:101], 0, s[20:21]
	global_load_dword v238, v[110:111], off
	s_mov_b32 s20, 0x9f000
	v_lshl_add_u64 v[110:111], v[100:101], 0, s[20:21]
	global_load_dword v239, v[110:111], off
	s_mov_b32 s20, 0xa2000
	v_lshl_add_u64 v[110:111], v[100:101], 0, s[20:21]
	global_load_dword v240, v[110:111], off
	s_mov_b32 s20, 0xa5000
	v_lshl_add_u64 v[110:111], v[100:101], 0, s[20:21]
	global_load_dword v241, v[110:111], off
	s_mov_b32 s20, 0xa8000
	v_lshl_add_u64 v[110:111], v[100:101], 0, s[20:21]
	global_load_dword v242, v[110:111], off
	s_mov_b32 s20, 0xab000
	v_lshl_add_u64 v[110:111], v[100:101], 0, s[20:21]
	global_load_dword v243, v[110:111], off
	s_mov_b32 s20, 0xae000
	v_lshl_add_u64 v[110:111], v[100:101], 0, s[20:21]
	global_load_dword v244, v[110:111], off
	s_mov_b32 s20, 0xb1000
	v_lshl_add_u64 v[110:111], v[100:101], 0, s[20:21]
	global_load_dword v245, v[110:111], off
	s_mov_b32 s20, 0xb4000
	v_lshl_add_u64 v[110:111], v[100:101], 0, s[20:21]
	global_load_dword v246, v[110:111], off
	s_mov_b32 s20, 0xb7000
	v_lshl_add_u64 v[110:111], v[100:101], 0, s[20:21]
	global_load_dword v164, v[110:111], off
	s_mov_b32 s20, 0xba000
	v_lshl_add_u64 v[110:111], v[100:101], 0, s[20:21]
	global_load_dword v165, v[110:111], off
	s_mov_b32 s20, 0xbd000
	v_lshl_add_u64 v[110:111], v[100:101], 0, s[20:21]
	global_load_dword v166, v[110:111], off
	s_mov_b64 s[18:19], 0
	v_mov_b32_e32 v74, v115
	v_mov_b32_e32 v103, v102
	v_mov_b32_e32 v104, v102
	v_mov_b32_e32 v105, v102
	v_mov_b32_e32 v106, v102
	v_mov_b32_e32 v107, v102
	v_mov_b32_e32 v108, v102
	v_mov_b32_e32 v109, v102
	v_mov_b32_e32 v99, v102
	s_waitcnt lgkmcnt(0)
	s_barrier
.LBB0_88:
	s_cmp_eq_u32 s18, 0
	s_cbranch_scc1 .Lmod_c0
	s_cmp_eq_u32 s18, 0x18000
	s_cbranch_scc1 .Lmod_c1
	s_cmp_eq_u32 s18, 0x30000
	s_cbranch_scc1 .Lmod_c2
	s_cmp_eq_u32 s18, 0x48000
	s_cbranch_scc1 .Lmod_c3
	s_cmp_eq_u32 s18, 0x60000
	s_cbranch_scc1 .Lmod_c4
	s_cmp_eq_u32 s18, 0x78000
	s_cbranch_scc1 .Lmod_c5
	s_cmp_eq_u32 s18, 0x90000
	s_cbranch_scc1 .Lmod_c6
.Lmod_c7:
	s_waitcnt vmcnt(0)
	v_mov_b32_e32 v132, v242
	v_mov_b32_e32 v134, v243
	v_mov_b32_e32 v136, v244
	v_mov_b32_e32 v138, v245
	v_mov_b32_e32 v140, v246
	v_mov_b32_e32 v142, v164
	v_mov_b32_e32 v144, v165
	v_mov_b32_e32 v110, v166
	s_branch .Lmod_body
.Lmod_c6:
	s_waitcnt vmcnt(8)
	v_mov_b32_e32 v132, v234
	v_mov_b32_e32 v134, v235
	v_mov_b32_e32 v136, v236
	v_mov_b32_e32 v138, v237
	v_mov_b32_e32 v140, v238
	v_mov_b32_e32 v142, v239
	v_mov_b32_e32 v144, v240
	v_mov_b32_e32 v110, v241
	s_branch .Lmod_body
.Lmod_c5:
	s_waitcnt vmcnt(16)
	v_mov_b32_e32 v132, v226
	v_mov_b32_e32 v134, v227
	v_mov_b32_e32 v136, v228
	v_mov_b32_e32 v138, v229
	v_mov_b32_e32 v140, v230
	v_mov_b32_e32 v142, v231
	v_mov_b32_e32 v144, v232
	v_mov_b32_e32 v110, v233
	s_branch .Lmod_body
.Lmod_c4:
	s_waitcnt vmcnt(24)
	v_mov_b32_e32 v132, v218
	v_mov_b32_e32 v134, v219
	v_mov_b32_e32 v136, v220
	v_mov_b32_e32 v138, v221
	v_mov_b32_e32 v140, v222
	v_mov_b32_e32 v142, v223
	v_mov_b32_e32 v144, v224
	v_mov_b32_e32 v110, v225
	s_branch .Lmod_body
.Lmod_c3:
	s_waitcnt vmcnt(32)
	v_mov_b32_e32 v132, v210
	v_mov_b32_e32 v134, v211
	v_mov_b32_e32 v136, v212
	v_mov_b32_e32 v138, v213
	v_mov_b32_e32 v140, v214
	v_mov_b32_e32 v142, v215
	v_mov_b32_e32 v144, v216
	v_mov_b32_e32 v110, v217
	s_branch .Lmod_body
.Lmod_c2:
	s_waitcnt vmcnt(40)
	v_mov_b32_e32 v132, v202
	v_mov_b32_e32 v134, v203
	v_mov_b32_e32 v136, v204
	v_mov_b32_e32 v138, v205
	v_mov_b32_e32 v140, v206
	v_mov_b32_e32 v142, v207
	v_mov_b32_e32 v144, v208
	v_mov_b32_e32 v110, v209
	s_branch .Lmod_body
.Lmod_c1:
	s_waitcnt vmcnt(48)
	v_mov_b32_e32 v132, v194
	v_mov_b32_e32 v134, v195
	v_mov_b32_e32 v136, v196
	v_mov_b32_e32 v138, v197
	v_mov_b32_e32 v140, v198
	v_mov_b32_e32 v142, v199
	v_mov_b32_e32 v144, v200
	v_mov_b32_e32 v110, v201
	s_branch .Lmod_body
.Lmod_c0:
	s_waitcnt vmcnt(56)
	v_mov_b32_e32 v132, v186
	v_mov_b32_e32 v134, v187
	v_mov_b32_e32 v136, v188
	v_mov_b32_e32 v138, v189
	v_mov_b32_e32 v140, v190
	v_mov_b32_e32 v142, v191
	v_mov_b32_e32 v144, v192
	v_mov_b32_e32 v110, v193
.Lmod_body:
	ds_read_b128 v[10:13], v74
	ds_read_b128 v[6:9], v74 offset:16
	ds_read_b128 v[2:5], v74 offset:4096
	ds_read_b128 v[14:17], v74 offset:4112
	ds_read_b128 v[42:45], v74 offset:8192
	ds_read_b128 v[34:37], v74 offset:8208
	ds_read_b128 v[26:29], v74 offset:12288
	ds_read_b128 v[18:21], v74 offset:12304
	ds_read_b128 v[58:61], v74 offset:16384
	ds_read_b128 v[50:53], v74 offset:16400
	ds_read_b128 v[30:33], v74 offset:20480
	ds_read_b128 v[22:25], v74 offset:20496
	ds_read_b128 v[70:73], v74 offset:24576
	ds_read_b128 v[62:65], v74 offset:24592
	ds_read_b128 v[38:41], v74 offset:28672
	ds_read_b128 v[46:49], v74 offset:28688
	ds_read_b128 v[66:69], v74 offset:32768
	ds_read_b128 v[54:57], v74 offset:32784
	s_waitcnt lgkmcnt(14)
	v_mov_b32_e32 v146, v10
	v_mov_b32_e32 v147, v2
	s_waitcnt lgkmcnt(13)
	v_mov_b32_e32 v148, v42
	s_waitcnt lgkmcnt(11)
	v_mov_b32_e32 v149, v26
	s_waitcnt lgkmcnt(9)
	v_mov_b32_e32 v150, v58
	s_waitcnt lgkmcnt(7)
	v_mov_b32_e32 v151, v30
	s_waitcnt lgkmcnt(5)
	v_mov_b32_e32 v152, v70
	s_waitcnt lgkmcnt(3)
	v_mov_b32_e32 v153, v38
	v_mov_b32_e32 v2, v11
	v_mov_b32_e32 v26, v43
	v_mov_b32_e32 v30, v59
	v_mov_b32_e32 v38, v71
	v_mov_b32_e32 v10, v12
	v_mov_b32_e32 v11, v4
	v_mov_b32_e32 v42, v44
	v_mov_b32_e32 v43, v28
	v_mov_b32_e32 v58, v60
	v_mov_b32_e32 v59, v32
	v_mov_b32_e32 v70, v72
	v_mov_b32_e32 v71, v40
	v_mov_b32_e32 v4, v13
	v_mov_b32_e32 v28, v45
	v_mov_b32_e32 v32, v61
	v_mov_b32_e32 v40, v73
	v_mov_b32_e32 v12, v6
	v_mov_b32_e32 v13, v14
	v_mov_b32_e32 v44, v34
	v_mov_b32_e32 v45, v18
	v_mov_b32_e32 v60, v50
	v_mov_b32_e32 v61, v22
	v_mov_b32_e32 v72, v62
	s_waitcnt lgkmcnt(2)
	v_mov_b32_e32 v73, v46
	v_mov_b32_e32 v14, v7
	v_mov_b32_e32 v18, v35
	v_mov_b32_e32 v22, v51
	v_mov_b32_e32 v46, v63
	v_mov_b32_e32 v6, v8
	v_mov_b32_e32 v7, v16
	v_mov_b32_e32 v34, v36
	v_mov_b32_e32 v35, v20
	v_mov_b32_e32 v50, v52
	v_mov_b32_e32 v51, v24
	v_mov_b32_e32 v62, v64
	v_mov_b32_e32 v63, v48
	v_mov_b32_e32 v16, v9
	v_mov_b32_e32 v20, v37
	v_mov_b32_e32 v24, v53
	v_mov_b32_e32 v48, v65
	s_add_u32 s18, s18, 0x18000
	s_addc_u32 s19, s19, 0
	v_add_u32_e32 v74, 32, v74
	s_cmp_eq_u32 s18, 0xc0000
	v_pk_fma_f32 v[8:9], v[132:133], v[146:147], v[102:103] op_sel_hi:[0,1,1]
	v_pk_fma_f32 v[36:37], v[132:133], v[148:149], v[104:105] op_sel_hi:[0,1,1]
	v_pk_fma_f32 v[52:53], v[132:133], v[150:151], v[106:107] op_sel_hi:[0,1,1]
	v_pk_fma_f32 v[64:65], v[132:133], v[152:153], v[108:109] op_sel_hi:[0,1,1]
	s_waitcnt lgkmcnt(1)
	v_fmac_f32_e32 v99, v132, v66
	v_pk_fma_f32 v[2:3], v[134:135], v[2:3], v[8:9] op_sel_hi:[0,1,1]
	v_pk_fma_f32 v[8:9], v[134:135], v[26:27], v[36:37] op_sel_hi:[0,1,1]
	v_pk_fma_f32 v[26:27], v[134:135], v[30:31], v[52:53] op_sel_hi:[0,1,1]
	v_pk_fma_f32 v[30:31], v[134:135], v[38:39], v[64:65] op_sel_hi:[0,1,1]
	v_fmac_f32_e32 v99, v134, v67
	v_pk_fma_f32 v[2:3], v[136:137], v[10:11], v[2:3] op_sel_hi:[0,1,1]
	v_pk_fma_f32 v[8:9], v[136:137], v[42:43], v[8:9] op_sel_hi:[0,1,1]
	v_pk_fma_f32 v[10:11], v[136:137], v[58:59], v[26:27] op_sel_hi:[0,1,1]
	v_pk_fma_f32 v[26:27], v[136:137], v[70:71], v[30:31] op_sel_hi:[0,1,1]
	v_fmac_f32_e32 v99, v136, v68
	v_pk_fma_f32 v[2:3], v[138:139], v[4:5], v[2:3] op_sel_hi:[0,1,1]
	v_pk_fma_f32 v[4:5], v[138:139], v[28:29], v[8:9] op_sel_hi:[0,1,1]
	v_pk_fma_f32 v[8:9], v[138:139], v[32:33], v[10:11] op_sel_hi:[0,1,1]
	v_pk_fma_f32 v[10:11], v[138:139], v[40:41], v[26:27] op_sel_hi:[0,1,1]
	v_fmac_f32_e32 v99, v138, v69
	v_pk_fma_f32 v[2:3], v[140:141], v[12:13], v[2:3] op_sel_hi:[0,1,1]
	v_pk_fma_f32 v[4:5], v[140:141], v[44:45], v[4:5] op_sel_hi:[0,1,1]
	v_pk_fma_f32 v[8:9], v[140:141], v[60:61], v[8:9] op_sel_hi:[0,1,1]
	v_pk_fma_f32 v[10:11], v[140:141], v[72:73], v[10:11] op_sel_hi:[0,1,1]
	s_waitcnt lgkmcnt(0)
	v_fmac_f32_e32 v99, v140, v54
	v_pk_fma_f32 v[2:3], v[142:143], v[14:15], v[2:3] op_sel_hi:[0,1,1]
	v_pk_fma_f32 v[4:5], v[142:143], v[18:19], v[4:5] op_sel_hi:[0,1,1]
	v_pk_fma_f32 v[8:9], v[142:143], v[22:23], v[8:9] op_sel_hi:[0,1,1]
	v_pk_fma_f32 v[10:11], v[142:143], v[46:47], v[10:11] op_sel_hi:[0,1,1]
	v_fmac_f32_e32 v99, v142, v55
	v_pk_fma_f32 v[2:3], v[144:145], v[6:7], v[2:3] op_sel_hi:[0,1,1]
	v_pk_fma_f32 v[4:5], v[144:145], v[34:35], v[4:5] op_sel_hi:[0,1,1]
	v_pk_fma_f32 v[6:7], v[144:145], v[50:51], v[8:9] op_sel_hi:[0,1,1]
	v_pk_fma_f32 v[8:9], v[144:145], v[62:63], v[10:11] op_sel_hi:[0,1,1]
	v_fmac_f32_e32 v99, v144, v56
	v_pk_fma_f32 v[102:103], v[110:111], v[16:17], v[2:3] op_sel_hi:[0,1,1]
	v_pk_fma_f32 v[104:105], v[110:111], v[20:21], v[4:5] op_sel_hi:[0,1,1]
	v_pk_fma_f32 v[106:107], v[110:111], v[24:25], v[6:7] op_sel_hi:[0,1,1]
	v_pk_fma_f32 v[108:109], v[110:111], v[48:49], v[8:9] op_sel_hi:[0,1,1]
	v_fmac_f32_e32 v99, v110, v57
	s_cbranch_scc0 .LBB0_88
	v_add_u32_e32 v2, 0x9000, v121
	ds_write2_b32 v2, v102, v103 offset1:32
	ds_write2_b32 v2, v104, v105 offset0:64 offset1:96
	ds_write2_b32 v2, v106, v107 offset0:128 offset1:160
	ds_write2_b32 v2, v108, v109 offset0:192 offset1:224
	ds_write_b32 v121, v99 offset:37888
	s_waitcnt lgkmcnt(0)
	s_barrier
	s_and_saveexec_b64 s[18:19], s[8:9]
	s_cbranch_execz .LBB0_55
	s_lshl_b32 s20, s74, 5
	v_or_b32_e32 v2, s20, v113
	v_ashrrev_i32_e32 v3, 31, v2
	v_lshl_add_u64 v[2:3], v[2:3], 2, s[30:31]
	global_load_dword v4, v[2:3], off
	ds_read_b32 v5, v122 offset:36864
	ds_read_b32 v6, v122 offset:38016
	ds_read_b32 v7, v122 offset:39168
	ds_read_b32 v8, v122 offset:40320
	ds_read_b32 v9, v122 offset:41472
	ds_read_b32 v10, v122 offset:42624
	ds_read_b32 v11, v122 offset:43776
	ds_read_b32 v12, v122 offset:44928
	ds_read_b32 v13, v122 offset:46080
	ds_read_b32 v14, v122 offset:47232
	ds_read_b32 v15, v122 offset:48384
	ds_read_b32 v16, v122 offset:49536
	ds_read_b32 v17, v122 offset:50688
	ds_read_b32 v18, v122 offset:51840
	ds_read_b32 v19, v122 offset:52992
	ds_read_b32 v20, v122 offset:54144
	s_waitcnt lgkmcnt(14)
	v_add_f32_e32 v5, 0, v5
	v_add_f32_e32 v5, v5, v6
	s_waitcnt lgkmcnt(13)
	v_add_f32_e32 v5, v5, v7
	s_waitcnt lgkmcnt(12)
	v_add_f32_e32 v5, v5, v8
	s_waitcnt lgkmcnt(11)
	v_add_f32_e32 v5, v5, v9
	s_waitcnt lgkmcnt(10)
	v_add_f32_e32 v5, v5, v10
	s_waitcnt lgkmcnt(9)
	v_add_f32_e32 v5, v5, v11
	s_waitcnt lgkmcnt(8)
	v_add_f32_e32 v5, v5, v12
	s_waitcnt lgkmcnt(7)
	v_add_f32_e32 v5, v5, v13
	s_waitcnt lgkmcnt(6)
	v_add_f32_e32 v5, v5, v14
	s_waitcnt lgkmcnt(5)
	v_add_f32_e32 v5, v5, v15
	s_waitcnt lgkmcnt(4)
	v_add_f32_e32 v5, v5, v16
	s_waitcnt lgkmcnt(3)
	v_add_f32_e32 v5, v5, v17
	s_waitcnt lgkmcnt(2)
	v_add_f32_e32 v5, v5, v18
	v_add_u32_e32 v2, s20, v116
	s_waitcnt lgkmcnt(1)
	v_add_f32_e32 v5, v5, v19
	v_ashrrev_i32_e32 v3, 31, v2
	s_waitcnt lgkmcnt(0)
	v_add_f32_e32 v5, v5, v20
	v_lshl_add_u64 v[2:3], v[2:3], 2, s[40:41]
	s_waitcnt vmcnt(0)
	v_add_f32_e32 v4, v5, v4
	global_store_dword v[2:3], v4, off
	s_branch .LBB0_55

.LBB0_683:
	s_and_b64 vcc, exec, s[74:75]
	s_mov_b32 s12, 0
	s_waitcnt lgkmcnt(0)
	s_barrier
	s_cbranch_vccnz .LBB0_735
	s_cmp_lg_u32 0x100, -1
	s_cselect_b32 s12, 0x100, 0
	s_add_i32 s14, s12, 0x3800
	s_addk_i32 s12, 0x2000
	v_add_u32_e32 v168, s12, v156
	s_lshl_b32 s12, s3, 2
	s_add_i32 s82, s82, s12
	s_mov_b32 s92, 0
	v_add_u32_e32 v167, s14, v156
	v_or_b32_e32 v169, 1, v157
	v_mov_b32_e32 v33, v32
	v_mov_b32_e32 v82, v32
	v_mov_b32_e32 v83, v32
	v_mov_b32_e32 v84, v32
	v_mov_b32_e32 v85, v32
	v_mov_b32_e32 v86, v32
	v_mov_b32_e32 v87, v32
	v_mov_b32_e32 v88, v32
	v_mov_b32_e32 v89, v32
	v_mov_b32_e32 v90, v32
	v_mov_b32_e32 v91, v32
	v_mov_b32_e32 v92, v32
	v_mov_b32_e32 v93, v32
	v_mov_b32_e32 v94, v32
	s_add_i32 s14, s76, 0x80
	s_sub_i32 s93, 0, s82
	s_mov_b32 s97, 0xa200
	s_movk_i32 s15, 0x5100
	s_mov_b32 s82, 3
	s_movk_i32 s83, 0xfe01
	v_mov_b32_e32 v95, v32
	v_lshl_add_u32 v182, v150, 1, v152
.LBB0_685:
	s_add_i32 s12, s83, 0x202
	s_cmp_lt_i32 s12, s9
	s_cselect_b64 s[16:17], -1, 0
	s_cmp_ge_i32 s12, s9
	s_mov_b32 s12, s15
	s_cbranch_scc1 .LBB0_689
	s_add_i32 s18, s14, 64
	s_ashr_i32 s19, s18, 31
	s_lshl_b64 s[20:21], s[18:19], 13
	s_add_u32 s15, s10, s20
	s_addc_u32 s21, s11, s21
	s_add_u32 s20, s15, s8
	s_addc_u32 s21, s21, 0
	s_add_u32 s20, s20, 0x1000
	s_addc_u32 s21, s21, 0
	v_mov_b32_e32 v153, v0
	global_load_dwordx4 v[136:139], v182, s[20:21] offset:1024
	s_and_saveexec_b64 s[20:21], s[6:7]
	s_cbranch_execz .LBB0_688
	v_lshl_add_u64 v[2:3], s[18:19], 2, v[154:155]
	global_load_dwordx4 v[128:131], v[2:3], off

.LBB0_689:
	s_add_i32 s15, s83, 0x201
	s_cmp_lt_i32 s15, s9
	s_cselect_b64 s[18:19], -1, 0
	s_cmp_ge_i32 s15, s9
	s_cbranch_scc1 .LBB0_691
	s_ashr_i32 s15, s14, 31
	s_lshl_b64 s[20:21], s[14:15], 13
	s_add_u32 s20, s95, s20
	s_addc_u32 s21, s96, s21
	s_add_u32 s20, s20, 0x1000
	s_addc_u32 s21, s21, 0
	v_mov_b32_e32 v153, v0
	global_load_dwordx4 v[132:135], v182, s[20:21] offset:2048

.LBB0_707:
	s_andn2_saveexec_b64 s[20:21], s[20:21]
	s_cbranch_execz .LBB0_709
	s_add_i32 s15, s12, 0x100
	v_add_u32_e32 v1, s15, v148
	s_waitcnt lgkmcnt(0)
	ds_read_b128 v[174:177], v1 offset:20704
	ds_read_b128 v[178:181], v1 offset:20672
	ds_read_b128 v[248:251], v1 offset:20640
	ds_read_b128 v[252:255], v1 offset:20608
	v_add_u32_e32 v153, s92, v167
	v_add_u32_e32 v1, s15, v162
	v_add_u32_e32 v10, v1, v163
	v_add_u32_e32 v14, v1, v164
	v_add_u32_e32 v15, v1, v165
	v_add_u32_e32 v1, v1, v166
	ds_read_b64_tr_b16 v[2:3], v153
	ds_read_b64_tr_b16 v[4:5], v153 offset:1536
	ds_read_b64_tr_b16 v[8:9], v153 offset:1600
	ds_read_b64_tr_b16 v[6:7], v153 offset:64
	ds_read_b128 v[10:13], v10 offset:4096
	ds_read_b128 v[104:107], v14 offset:4096
	ds_read_b128 v[108:111], v15 offset:4096
	ds_read_b128 v[140:143], v1 offset:4096
	s_waitcnt lgkmcnt(11)
	v_sub_f32_e32 v49, v95, v177
	v_sub_f32_e32 v48, v94, v176
	v_sub_f32_e32 v47, v93, v175
	v_sub_f32_e32 v46, v92, v174
	s_waitcnt lgkmcnt(10)
	v_sub_f32_e32 v45, v91, v181
	v_sub_f32_e32 v44, v90, v180
	v_sub_f32_e32 v43, v89, v179
	v_sub_f32_e32 v42, v88, v178
	s_waitcnt lgkmcnt(9)
	v_sub_f32_e32 v41, v87, v251
	v_sub_f32_e32 v40, v86, v250
	v_sub_f32_e32 v39, v85, v249
	v_sub_f32_e32 v38, v84, v248
	s_waitcnt lgkmcnt(8)
	v_sub_f32_e32 v37, v83, v255
	v_sub_f32_e32 v36, v82, v254
	v_sub_f32_e32 v35, v33, v253
	v_sub_f32_e32 v34, v32, v252
	s_nop 1
	s_setprio 1
	s_waitcnt lgkmcnt(3)
	v_mfma_f32_32x32x16_bf16 v[34:49], v[10:13], v[120:123], v[34:49]
	v_exp_f32_e32 v14, v72
	v_exp_f32_e32 v15, v80
	s_waitcnt lgkmcnt(2)
	v_mfma_f32_32x32x16_bf16 v[34:49], v[104:107], v[112:115], v[34:49]
	ds_read_b64_tr_b16 v[10:11], v153 offset:3072
	ds_read_b64_tr_b16 v[12:13], v153 offset:4608
	ds_read_b64_tr_b16 v[104:105], v153 offset:3136
	ds_read_b64_tr_b16 v[106:107], v153 offset:4672
	v_mfma_f32_32x32x16_bf16 v[50:65], v[2:5], v[96:99], v[50:65]
	v_exp_f32_e32 v2, v66
	v_exp_f32_e32 v4, v67
	v_exp_f32_e32 v3, v74
	v_exp_f32_e32 v5, v75
	v_mfma_f32_32x32x16_bf16 v[16:31], v[6:9], v[96:99], v[16:31]
	v_exp_f32_e32 v6, v68
	v_exp_f32_e32 v8, v69
	v_exp_f32_e32 v7, v76
	v_exp_f32_e32 v9, v77
	s_waitcnt lgkmcnt(5)
	v_mfma_f32_32x32x16_bf16 v[34:49], v[108:111], v[116:119], v[34:49]
	s_waitcnt lgkmcnt(2)
	v_mfma_f32_32x32x16_bf16 v[50:65], v[10:13], v[100:103], v[50:65]
	v_exp_f32_e32 v10, v70
	v_exp_f32_e32 v12, v71
	v_exp_f32_e32 v11, v78
	v_exp_f32_e32 v13, v79
	s_waitcnt lgkmcnt(0)
	v_mfma_f32_32x32x16_bf16 v[16:31], v[104:107], v[100:103], v[16:31]
	v_exp_f32_e32 v102, v73
	v_exp_f32_e32 v103, v81
	v_add_f32_e32 v1, v14, v15
	v_add_f32_e32 v1, v1, v2
	v_add_f32_e32 v1, v1, v4
	v_add_f32_e32 v1, v1, v3
	v_add_f32_e32 v1, v1, v5
	v_add_f32_e32 v1, v1, v6
	v_add_f32_e32 v1, v1, v8
	v_add_f32_e32 v1, v1, v7
	v_add_f32_e32 v1, v1, v9
	v_add_f32_e32 v1, v1, v10
	v_add_f32_e32 v1, v1, v12
	v_add_f32_e32 v1, v1, v11
	v_add_f32_e32 v1, v1, v13
	v_add_f32_e32 v1, v1, v102
	v_add_f32_e32 v1, v1, v103
	v_add_f32_e32 v160, v160, v1
	v_mfma_f32_32x32x16_bf16 v[34:49], v[140:143], v[124:127], v[34:49]
	v_cvt_pk_bf16_f32 v98, v10, v12
	v_cvt_pk_bf16_f32 v96, v2, v4
	v_cvt_pk_bf16_f32 v97, v6, v8
	v_cvt_pk_bf16_f32 v99, v14, v102
	v_cvt_pk_bf16_f32 v100, v3, v5
	v_cvt_pk_bf16_f32 v101, v7, v9
	v_cvt_pk_bf16_f32 v102, v11, v13
	v_cvt_pk_bf16_f32 v103, v15, v103
	s_setprio 0

.LBB0_718:
	s_add_i32 s15, s97, 0x100
	v_add_u32_e32 v1, s15, v148
	s_waitcnt lgkmcnt(0)
	ds_read_b128 v[174:177], v1 offset:20576
	ds_read_b128 v[178:181], v1 offset:20544
	ds_read_b128 v[248:251], v1 offset:20512
	ds_read_b128 v[252:255], v1 offset:20480
	v_add_u32_e32 v153, s12, v168
	v_add_u32_e32 v1, s15, v162
	v_add_u32_e32 v10, v1, v163
	v_add_u32_e32 v14, v1, v164
	v_add_u32_e32 v15, v1, v165
	v_add_u32_e32 v1, v1, v166
	ds_read_b64_tr_b16 v[2:3], v153
	ds_read_b64_tr_b16 v[4:5], v153 offset:1536
	ds_read_b64_tr_b16 v[8:9], v153 offset:1600
	ds_read_b64_tr_b16 v[6:7], v153 offset:64
	ds_read_b128 v[10:13], v10
	ds_read_b128 v[104:107], v14
	ds_read_b128 v[108:111], v15
	ds_read_b128 v[140:143], v1
	s_waitcnt lgkmcnt(11)
	v_sub_f32_e32 v81, v95, v177
	v_sub_f32_e32 v80, v94, v176
	v_sub_f32_e32 v79, v93, v175
	v_sub_f32_e32 v78, v92, v174
	s_waitcnt lgkmcnt(10)
	v_sub_f32_e32 v77, v91, v181
	v_sub_f32_e32 v76, v90, v180
	v_sub_f32_e32 v75, v89, v179
	v_sub_f32_e32 v74, v88, v178
	s_waitcnt lgkmcnt(9)
	v_sub_f32_e32 v73, v87, v251
	v_sub_f32_e32 v72, v86, v250
	v_sub_f32_e32 v71, v85, v249
	v_sub_f32_e32 v70, v84, v248
	s_waitcnt lgkmcnt(8)
	v_sub_f32_e32 v69, v83, v255
	v_sub_f32_e32 v68, v82, v254
	v_sub_f32_e32 v67, v33, v253
	v_sub_f32_e32 v66, v32, v252
	s_nop 1
	s_setprio 1
	s_waitcnt lgkmcnt(3)
	v_mfma_f32_32x32x16_bf16 v[66:81], v[10:13], v[120:123], v[66:81]
	v_exp_f32_e32 v14, v40
	v_exp_f32_e32 v15, v48
	s_waitcnt lgkmcnt(2)
	v_mfma_f32_32x32x16_bf16 v[66:81], v[104:107], v[112:115], v[66:81]
	ds_read_b64_tr_b16 v[10:11], v153 offset:3072
	ds_read_b64_tr_b16 v[12:13], v153 offset:4608
	ds_read_b64_tr_b16 v[104:105], v153 offset:3136
	ds_read_b64_tr_b16 v[106:107], v153 offset:4672
	v_mfma_f32_32x32x16_bf16 v[50:65], v[2:5], v[96:99], v[50:65]
	v_exp_f32_e32 v2, v34
	v_exp_f32_e32 v4, v35
	v_exp_f32_e32 v3, v42
	v_exp_f32_e32 v5, v43
	v_mfma_f32_32x32x16_bf16 v[16:31], v[6:9], v[96:99], v[16:31]
	v_exp_f32_e32 v6, v36
	v_exp_f32_e32 v8, v37
	v_exp_f32_e32 v7, v44
	v_exp_f32_e32 v9, v45
	s_waitcnt lgkmcnt(5)
	v_mfma_f32_32x32x16_bf16 v[66:81], v[108:111], v[116:119], v[66:81]
	s_waitcnt lgkmcnt(2)
	v_mfma_f32_32x32x16_bf16 v[50:65], v[10:13], v[100:103], v[50:65]
	v_exp_f32_e32 v10, v38
	v_exp_f32_e32 v12, v39
	v_exp_f32_e32 v11, v46
	v_exp_f32_e32 v13, v47
	s_waitcnt lgkmcnt(0)
	v_mfma_f32_32x32x16_bf16 v[16:31], v[104:107], v[100:103], v[16:31]
	v_exp_f32_e32 v102, v41
	v_exp_f32_e32 v103, v49
	v_add_f32_e32 v1, v14, v15
	v_add_f32_e32 v1, v1, v2
	v_add_f32_e32 v1, v1, v4
	v_add_f32_e32 v1, v1, v3
	v_add_f32_e32 v1, v1, v5
	v_add_f32_e32 v1, v1, v6
	v_add_f32_e32 v1, v1, v8
	v_add_f32_e32 v1, v1, v7
	v_add_f32_e32 v1, v1, v9
	v_add_f32_e32 v1, v1, v10
	v_add_f32_e32 v1, v1, v12
	v_add_f32_e32 v1, v1, v11
	v_add_f32_e32 v1, v1, v13
	v_add_f32_e32 v1, v1, v102
	v_add_f32_e32 v1, v1, v103
	v_add_f32_e32 v160, v160, v1
	v_mfma_f32_32x32x16_bf16 v[66:81], v[140:143], v[124:127], v[66:81]
	v_cvt_pk_bf16_f32 v98, v10, v12
	v_cvt_pk_bf16_f32 v96, v2, v4
	v_cvt_pk_bf16_f32 v97, v6, v8
	v_cvt_pk_bf16_f32 v99, v14, v102
	v_cvt_pk_bf16_f32 v100, v3, v5
	v_cvt_pk_bf16_f32 v101, v7, v9
	v_cvt_pk_bf16_f32 v102, v11, v13
	v_cvt_pk_bf16_f32 v103, v15, v103
	s_setprio 0
	s_or_b64 exec, exec, s[20:21]
	s_andn2_b64 vcc, exec, s[16:17]
	s_cbranch_vccz .LBB0_732
